# P2a gla chunk items: next item's raw k/v/glr loads prefetched into spare VGPRs during the current item (cross-item register prefetch)
# speedup vs baseline: 1.0024x; 1.0024x over previous
; __device__ __forceinline__ unsigned pk2(float lo, float hi) { unsigned r; asm("v_cvt_pk_bf16_f32 %0, %1, %2" : "=v"(r) : "v"(lo), "v"(hi)); return r; }
; __device__ __forceinline__ void sgu_prompt_item(int item, const u16* PROJ, u16* MIXIN, const float* gln, const float* bln, const float* wsp, const float* bsp, LAS unsigned char* lds, int& hh_cached) {
;     ...
;         const int t = tid >> 2, s0 = (tid & 3) * 32; const float* wp = wsp + ((size_t)hh * 128 + t) * 128 + s0;
; #pragma unroll
;         for (int q = 0; q < 4; ++q) { const f32x4 a = *(const f32x4*)(wp + 8 * q), b = *(const f32x4*)(wp + 8 * q + 4); const int s = s0 + 8 * q;
;             u32x4 o; o.x = pk2(s <= t ? a.x : 0.f, s + 1 <= t ? a.y : 0.f); o.y = pk2(s + 2 <= t ? a.z : 0.f, s + 3 <= t ? a.w : 0.f);
;             o.z = pk2(s + 4 <= t ? b.x : 0.f, s + 5 <= t ? b.y : 0.f); o.w = pk2(s + 6 <= t ? b.z : 0.f, s + 7 <= t ? b.w : 0.f);
; __global__ void __launch_bounds__(512, 2) fwd_kernel(Args args) {
;     ...
;     if (IN(2)) {
;         u16* MIXIN = H; float* GS = (float*)(ws + WS_BIG2); float* GDEC = (float*)(ws + WS_BIG2 + 40 * MiB); u16* GSB = (u16*)(ws + WS_BIG2 + 48 * MiB);
;         int hh_cached = -1;
;         GateW gwt; gwt.h = -1; gwt.bgd = 0.f;
; #pragma unroll
;         for (int r = 0; r < 16; ++r) gwt.wg[r] = 0.f;
;         for (int it = bid; it < 2048; it += G) {
;             if (it < 512) sgu_prompt_item(it, PROJ, MIXIN, args.in[I_GSGULN], args.in[I_BSGULN], args.in[I_WSPAT], args.in[I_BSPAT], lds, hh_cached);
.LBB0_220:
	s_cmp_lt_i32 s94, 3
	s_cselect_b64 s[8:9], -1, 0
	s_waitcnt lgkmcnt(0)
	s_add_u32 s28, s92, 0xa300000
	s_addc_u32 s29, s93, 0
	s_and_b64 s[78:79], s[8:9], s[6:7]
	s_andn2_b64 vcc, exec, s[78:79]
	s_cbranch_vccnz .LBB0_371
	s_add_u32 s12, s92, 0xcb00000
	s_addc_u32 s13, s93, 0
	s_add_i32 s3, 0, 0x16400
	s_mov_b32 s7, 0
	v_lshl_add_u32 v33, v128, 2, s3
	s_cmpk_gt_i32 s2, 0x7ff
	v_lshrrev_b32_e32 v32, 4, v129
	v_lshrrev_b32_e32 v34, 3, v128
	v_lshlrev_b32_e32 v65, 1, v129
	v_lshrrev_b32_e32 v61, 2, v129
	s_cbranch_scc1 .LBB0_247
	s_load_dwordx8 s[56:63], s[0:1], 0xc0
	v_writelane_b32 v237, s78, 13
	s_movk_i32 s3, 0x100
	v_lshrrev_b32_e32 v67, 6, v129
	v_writelane_b32 v237, s79, 14
	v_writelane_b32 v237, s90, 15
	v_and_b32_e32 v69, 0x7f, v129
	v_cmp_gt_u32_e64 s[8:9], s3, v129
	v_lshlrev_b32_e32 v52, 2, v69
	v_mov_b32_e32 v53, 0
	v_writelane_b32 v237, s8, 16
	v_lshlrev_b32_e32 v2, 2, v128
	v_mul_u32_u24_e32 v0, 0x300, v67
	v_add_u32_e32 v7, 0x200, v129
	v_writelane_b32 v237, s9, 17
	v_add3_u32 v71, 0, v0, v2
	s_waitcnt lgkmcnt(0)
	v_lshl_add_u64 v[0:1], s[62:63], 0, v[52:53]
	s_mov_b64 s[8:9], 0x4300000
	v_lshrrev_b32_e32 v68, 4, v7
	v_add_u32_e32 v7, 0x600, v129
	v_lshl_add_u64 v[58:59], v[0:1], 0, s[8:9]
	v_cmp_eq_u32_e64 s[8:9], 0, v128
	v_lshrrev_b32_e32 v72, 4, v7
	v_lshlrev_b32_e32 v7, 5, v129
	v_writelane_b32 v237, s8, 18
	v_and_b32_e32 v7, 0x60, v7
	v_or_b32_e32 v10, 2, v7
	v_writelane_b32 v237, s9, 19
	v_cmp_gt_u32_e64 s[8:9], v7, v61
	v_mul_u32_u24_e32 v9, 0x110, v61
	v_mov_b32_e32 v3, v53
	v_writelane_b32 v237, s8, 20
	v_lshl_add_u64 v[56:57], s[36:37], 0, v[2:3]
	v_lshlrev_b32_e32 v1, 3, v129
	v_writelane_b32 v237, s9, 21
	v_cmp_lt_u32_e64 s[8:9], v7, v61
	v_lshl_add_u64 v[62:63], s[12:13], 0, v[2:3]
	v_lshrrev_b32_e32 v2, 1, v129
	v_writelane_b32 v237, s8, 22
	v_lshrrev_b32_e32 v107, 3, v129
	v_and_b32_e32 v0, 56, v1
	v_writelane_b32 v237, s9, 23
	v_cmp_gt_u32_e64 s[8:9], v10, v61
	v_or_b32_e32 v10, 3, v7
	s_movk_i32 s3, 0x108
	v_writelane_b32 v237, s8, 24
	v_lshl_add_u32 v112, v128, 1, 0
	s_movk_i32 s6, 0x8e
	v_writelane_b32 v237, s9, 25
	v_cmp_gt_u32_e64 s[8:9], v10, v61
	v_or_b32_e32 v10, 4, v7
	v_and_b32_e32 v2, 24, v2
	v_writelane_b32 v237, s8, 26
	v_and_b32_e32 v12, 3, v129
	v_and_b32_e32 v14, 0xe0, v61
	v_writelane_b32 v237, s9, 27
	v_cmp_gt_u32_e64 s[8:9], v10, v61
	v_or_b32_e32 v10, 5, v7
	v_lshl_add_u64 v[54:55], s[20:21], 0, v[52:53]
	v_writelane_b32 v237, s8, 28
	v_add_u32_e32 v106, 0, v52
	v_and_b32_e32 v60, 0x78, v1
	v_writelane_b32 v237, s9, 29
	v_cmp_gt_u32_e64 s[8:9], v10, v61
	v_or_b32_e32 v10, 6, v7
	v_and_b32_e32 v1, 14, v65
	v_writelane_b32 v237, s8, 30
	s_add_i32 s97, 0, 0x15400
	v_lshlrev_b32_e32 v4, 7, v107
	v_writelane_b32 v237, s9, 31
	v_cmp_gt_u32_e64 s[8:9], v10, v61
	v_or_b32_e32 v10, 7, v7
	v_lshlrev_b32_e32 v5, 1, v0
	v_writelane_b32 v237, s8, 32
	v_mad_u32_u24 v113, v128, s6, v112
	v_and_b32_e32 v64, 15, v129
	v_writelane_b32 v237, s9, 33
	v_cmp_gt_u32_e64 s[8:9], v10, v61
	v_lshlrev_b32_e32 v10, 1, v7
	v_add3_u32 v120, 0, v9, v10
	v_writelane_b32 v237, s8, 34
	v_or_b32_e32 v10, 8, v7
	v_mad_u32_u24 v114, v2, s3, 0
	v_writelane_b32 v237, s9, 35
	v_cmp_gt_u32_e64 s[8:9], v10, v61
	v_lshl_add_u32 v3, v2, 1, 0
	s_movk_i32 s3, 0x90
	v_writelane_b32 v237, s8, 36
	v_lshlrev_b32_e32 v52, 2, v7
	s_movk_i32 s6, 0x110
	v_writelane_b32 v237, s9, 37
	v_cmp_lt_u32_e64 s[8:9], v10, v61
	v_or_b32_e32 v10, 10, v7
	v_cmp_eq_u32_e64 s[76:77], 0, v12
	v_writelane_b32 v237, s8, 38
	v_mul_u32_u24_e32 v16, 0x110, v69
	v_lshlrev_b32_e32 v121, 3, v14
	v_writelane_b32 v237, s9, 39
	v_cmp_gt_u32_e64 s[8:9], v10, v61
	v_or_b32_e32 v10, 11, v7
	v_mul_u32_u24_e32 v17, 0x110, v14
	v_writelane_b32 v237, s8, 40
	v_lshlrev_b32_e32 v14, 1, v14
	v_lshl_add_u32 v109, v1, 2, s97
	v_writelane_b32 v237, s9, 41
	v_cmp_gt_u32_e64 s[8:9], v10, v61
	v_or_b32_e32 v10, 12, v7
	v_add3_u32 v110, 0, v4, v5
	v_writelane_b32 v237, s8, 42
	v_mul_u32_u24_e32 v4, 0x108, v32
	v_lshlrev_b32_e32 v5, 1, v60
	v_writelane_b32 v237, s9, 43
	v_cmp_gt_u32_e64 s[8:9], v10, v61
	v_or_b32_e32 v10, 13, v7
	v_mad_u32_u24 v115, v64, s3, v3
	v_writelane_b32 v237, s8, 44
	v_lshlrev_b32_e32 v2, 7, v64
	v_lshl_add_u64 v[74:75], s[46:47], 0, v[52:53]
	v_writelane_b32 v237, s9, 45
	v_cmp_gt_u32_e64 s[8:9], v10, v61
	v_or_b32_e32 v10, 14, v7
	v_add3_u32 v125, 0, v16, v14
	v_writelane_b32 v237, s8, 46
	v_or_b32_e32 v14, 31, v61
	v_mad_u32_u24 v141, v64, s6, v3
; __global__ void __launch_bounds__(512, 2) fwd_kernel(Args args) {
;     ...
;     if (IN(2)) {
;         u16* MIXIN = H; float* GS = (float*)(ws + WS_BIG2); float* GDEC = (float*)(ws + WS_BIG2 + 40 * MiB); u16* GSB = (u16*)(ws + WS_BIG2 + 48 * MiB);
;         int hh_cached = -1;
;         GateW gwt; gwt.h = -1; gwt.bgd = 0.f;
; #pragma unroll
;         for (int r = 0; r < 16; ++r) gwt.wg[r] = 0.f;
;         for (int it = bid; it < 2048; it += G) {
;             if (it < 512) sgu_prompt_item(it, PROJ, MIXIN, args.in[I_GSGULN], args.in[I_BSGULN], args.in[I_WSPAT], args.in[I_BSPAT], lds, hh_cached);
	v_writelane_b32 v237, s9, 47
	v_cmp_gt_u32_e64 s[8:9], v10, v61
	v_or_b32_e32 v10, 15, v7
	v_lshlrev_b32_e32 v52, 1, v1
	v_writelane_b32 v237, s8, 48
	v_mul_u32_u24_e32 v1, 0x110, v64
	v_and_b32_e32 v3, 48, v129
	v_writelane_b32 v237, s9, 49
	v_cmp_gt_u32_e64 s[8:9], v10, v61
	v_or_b32_e32 v10, 16, v7
	v_lshlrev_b32_e32 v78, 1, v0
	v_writelane_b32 v237, s8, 50
	v_add3_u32 v111, 0, v4, v5
	v_or_b32_e32 v4, 0x800, v2
	v_writelane_b32 v237, s9, 51
	v_cmp_gt_u32_e64 s[8:9], v10, v61
	v_or_b32_e32 v6, 0x1000, v2
	v_or_b32_e32 v8, 0x1800, v2
	v_writelane_b32 v237, s8, 52
	v_mul_u32_u24_e32 v11, 0x110, v72
	v_lshlrev_b32_e32 v140, 3, v14
	v_writelane_b32 v237, s9, 53
	v_cmp_lt_u32_e64 s[8:9], v10, v61
	v_or_b32_e32 v10, 18, v7
	v_mul_u32_u24_e32 v14, 0x110, v14
	v_writelane_b32 v237, s8, 54
	v_add3_u32 v1, v1, v3, 0
	v_add_u32_e32 v108, 32, v32
	v_writelane_b32 v237, s9, 55
	v_cmp_gt_u32_e64 s[8:9], v10, v61
	v_or_b32_e32 v10, 19, v7
	v_and_b32_e32 v66, 12, v61
	v_writelane_b32 v237, s8, 56
	v_add_u32_e32 v116, 0x900, v115
	v_add_u32_e32 v117, 0x1200, v115
	v_writelane_b32 v237, s9, 57
	v_cmp_gt_u32_e64 s[8:9], v10, v61
	v_or_b32_e32 v10, 20, v7
	s_movk_i32 s3, 0x1000
	v_writelane_b32 v237, s8, 58
	v_add_u32_e32 v118, 0x1b00, v115
	v_or_b32_e32 v70, 64, v32
	v_writelane_b32 v237, s9, 59
	v_cmp_gt_u32_e64 s[8:9], v10, v61
	v_or_b32_e32 v10, 21, v7
	v_mov_b32_e32 v73, v53
	v_writelane_b32 v237, s8, 60
	v_lshlrev_b32_e32 v119, 7, v61
	v_or_b32_e32 v122, 16, v121
	v_writelane_b32 v237, s9, 61
	v_cmp_gt_u32_e64 s[8:9], v10, v61
	v_or_b32_e32 v10, 22, v7
	v_or_b32_e32 v123, 32, v121
	v_writelane_b32 v237, s8, 62
	v_or_b32_e32 v124, 48, v121
	v_or_b32_e32 v126, 64, v121
	v_writelane_b32 v237, s9, 63
	v_cmp_gt_u32_e64 s[8:9], v10, v61
	v_or_b32_e32 v10, 23, v7
	v_or_b32_e32 v127, 0x50, v121
	v_writelane_b32 v236, s8, 0
	v_or_b32_e32 v130, 0x60, v121
	v_or_b32_e32 v131, 0x70, v121
	v_writelane_b32 v236, s9, 1
	v_cmp_gt_u32_e64 s[8:9], v10, v61
	v_or_b32_e32 v10, 24, v7
	v_or_b32_e32 v132, 0x80, v121
	v_writelane_b32 v236, s8, 2
	v_or_b32_e32 v133, 0x90, v121
	v_or_b32_e32 v134, 0xa0, v121
	v_writelane_b32 v236, s9, 3
	v_cmp_gt_u32_e64 s[8:9], v10, v61
	v_or_b32_e32 v135, 0xb0, v121
	v_or_b32_e32 v136, 0xc0, v121
	v_writelane_b32 v236, s8, 4
	v_or_b32_e32 v137, 0xd0, v121
	v_or_b32_e32 v138, 0xe0, v121
	v_writelane_b32 v236, s9, 5
	v_cmp_lt_u32_e64 s[8:9], v10, v61
	v_or_b32_e32 v10, 26, v7
	v_or_b32_e32 v139, 0xf0, v121
	v_writelane_b32 v236, s8, 6
	v_or_b32_e32 v142, 0x2c00200, v69
	v_lshl_add_u64 v[76:77], s[4:5], 0, v[52:53]
	v_writelane_b32 v236, s9, 7
	v_cmp_gt_u32_e64 s[8:9], v10, v61
	v_or_b32_e32 v10, 27, v7
	v_cmp_gt_u32_e64 s[66:67], v10, v61
	v_writelane_b32 v236, s8, 8
	v_or_b32_e32 v10, 28, v7
	v_cmp_gt_u32_e64 s[68:69], v10, v61
	v_writelane_b32 v236, s9, 9
	s_add_i32 s8, 0, 0x11000
	v_or_b32_e32 v10, 29, v7
	v_lshl_add_u32 v13, v12, 6, s8
	v_lshlrev_b32_e32 v12, 3, v61
	v_cmp_gt_u32_e64 s[70:71], v10, v61
	v_or_b32_e32 v10, 30, v7
	v_or_b32_e32 v7, 31, v7
	v_add_u32_e32 v0, 0, v12
	v_cmp_gt_u32_e64 s[72:73], v10, v61
	v_cmp_gt_u32_e64 s[74:75], v7, v61
	v_add_u32_e32 v5, s8, v5
	v_mul_u32_u24_e32 v7, 0x110, v32
	v_mul_u32_u24_e32 v10, 0x110, v68
	v_lshl_add_u32 v15, v69, 1, s8
	v_add_u32_e32 v149, 0x19800, v0
	v_mbcnt_lo_u32_b32 v0, -1, 0
	v_add_u32_e32 v143, 0x8800, v1
	s_mov_b32 s33, -1
	s_mov_b32 s20, 0xbfb8aa3b
	s_mov_b32 s21, 0x800000
	s_mov_b32 s8, 0x3f317217
	s_mov_b32 s9, 0x7f800000
	v_mov_b32_e32 v144, 0x358637bd
	s_movk_i32 s30, 0x1600
	s_mov_b32 s31, 0x5040100
	v_lshlrev_b32_e32 v80, 2, v2
	v_lshlrev_b32_e32 v82, 2, v4
	v_lshlrev_b32_e32 v84, 2, v6
	v_lshlrev_b32_e32 v86, 2, v8
	v_add_u32_e32 v145, v5, v7
	v_add_u32_e32 v146, v5, v10
	v_add_u32_e32 v147, v5, v11
	v_add_u32_e32 v148, v13, v9
	v_add_u32_e32 v150, v15, v17
	v_add_u32_e32 v151, v15, v14
	v_mov_b32_e32 v152, 0x41b17218
	v_mbcnt_hi_u32_b32 v153, -1, v0
	v_mov_b32_e32 v154, 0x1600
	v_mov_b32_e32 v35, 0
	s_mov_b32 s50, s2
	s_mov_b32 s51, -1
	v_mov_b32_e32 v38, v53
	v_mov_b32_e32 v39, v53
	v_mov_b32_e32 v40, v53
	v_mov_b32_e32 v41, v53
	v_mov_b32_e32 v42, v53
	v_mov_b32_e32 v43, v53
	v_mov_b32_e32 v44, v53
	v_mov_b32_e32 v45, v53
	v_mov_b32_e32 v36, v53
	v_mov_b32_e32 v37, v53
	v_mov_b32_e32 v46, v53
	v_mov_b32_e32 v47, v53
	v_mov_b32_e32 v48, v53
	v_mov_b32_e32 v49, v53
	v_mov_b32_e32 v50, v53
	v_mov_b32_e32 v51, v53
	s_mov_b64 s[64:65], s[88:89]
	s_mov_b32 s99, -1
	s_branch .LBB0_224

; #define LAS __attribute__((address_space(3)))
; __device__ __forceinline__ float bf2f(unsigned b) { return __uint_as_float(b << 16); }
; __device__ __forceinline__ float logsig(float x) { return fminf(x, 0.f) - __logf(1.f + __expf(-fabsf(x))); }
; template <int MODE>
; __device__ __forceinline__ void gla_chunk_item(int item, const u16* PROJ, u16* MIXIN, const float* wgate, const float* bgate, const float* ggla, float* GS, float* GDEC, const u16* GSB, LAS unsigned char* lds, GateW& gw_) {
;     ...
;     const int qt_ = tid >> 3, qd_ = (tid & 7) * 8;
;     const int vt_ = tid >> 4, ve_ = (tid & 15) * 8;
;     u32x4 qraw, kraw, vraw0, vraw1, sraw[2];
;     if (MODE == 1) qraw = *(const u32x4*)(PROJ + (row0 + qt_) * NPROJ + C_Q + h * 64 + qd_);
;     kraw = *(const u32x4*)(PROJ + (row0 + qt_) * NPROJ + C_K + h * 64 + qd_);
;     vraw0 = *(const u32x4*)(PROJ + (row0 + vt_) * NPROJ + C_V + h * 128 + ve_);
;     vraw1 = *(const u32x4*)(PROJ + (row0 + 32 + vt_) * NPROJ + C_V + h * 128 + ve_);
;     const unsigned glr = *(const unsigned*)(PROJ + (row0 + seg * 8 + (lane >> 3)) * NPROJ + C_GLR + (lane & 7) * 2);
;     if (MODE == 1) {
; #pragma unroll
;         for (int i = 0; i < 2; ++i) sraw[i] = ((const u32x4*)(GSB + (size_t)item * 8192))[tid + 512 * i];
;     }
;     GLR[(seg * 8 + (lane >> 3)) * 16 + (lane & 7) * 2] = bf2f(glr & 0xffffu);
;     GLR[(seg * 8 + (lane >> 3)) * 16 + (lane & 7) * 2 + 1] = bf2f(glr >> 16);
;     float bl[8], run = 0.f;
; #pragma unroll
;     for (int tt = 0; tt < 8; ++tt) {
;         const LAS f32x4* gp = (const LAS f32x4*)(GLR + (seg * 8 + tt) * 16);
;         float logit = gw_.bgd;
; #pragma unroll
;         for (int r4 = 0; r4 < 4; ++r4) { const f32x4 gv = gp[r4]; logit += gv.x * gw_.wg[4 * r4] + gv.y * gw_.wg[4 * r4 + 1] + gv.z * gw_.wg[4 * r4 + 2] + gv.w * gw_.wg[4 * r4 + 3]; }
;         run += logsig(logit) * (1.f / 16.f); bl[tt] = run;
;     }
;     SEG[seg * 64 + d] = run;
.LBB0_244:
	s_add_i32 s6, s50, 0xfffffe00
	s_lshl_b32 s58, s6, 4
	s_lshl_b32 s59, s6, 6
	s_and_b32 s58, s58, 0x3800
	s_and_b32 s59, s59, 0x7c0
	s_or_b32 s60, s58, s59
	v_add_u32_e32 v0, s60, v107
	v_mul_u32_u24_e32 v0, 0xb00, v0
	v_lshlrev_b32_e32 v52, 1, v0
	s_lshr_b32 s54, s55, 6
	v_lshl_add_u64 v[0:1], s[4:5], 0, v[52:53]
	s_lshl_b32 s58, s57, 1
	s_mov_b32 s59, s7
	v_or_b32_e32 v4, s60, v32
	v_mov_b64_e32 v[8:9], s[4:5]
	v_add_u32_e32 v10, s60, v108
	v_lshl_add_u64 v[0:1], v[0:1], 0, s[58:59]
	v_mad_u64_u32 v[4:5], s[58:59], v4, s30, v[8:9]
	s_lshl_b32 s56, s56, 8
	s_mov_b32 s57, s7
	v_mad_u64_u32 v[8:9], s[58:59], v10, s30, v[8:9]
	s_lshl_b32 s80, s54, 3
	v_lshl_add_u64 v[4:5], v[4:5], 0, s[56:57]
	v_lshlrev_b32_e32 v52, 1, v60
	v_lshl_add_u64 v[8:9], v[8:9], 0, s[56:57]
	s_add_i32 s56, s80, s60
	v_lshl_add_u64 v[4:5], v[4:5], 0, v[52:53]
	v_lshl_add_u64 v[8:9], v[8:9], 0, v[52:53]
	v_or_b32_e32 v52, s56, v34
	v_mad_u64_u32 v[102:103], s[56:57], v52, s30, v[76:77]
	v_mov_b32_e32 v79, v53
	v_lshl_add_u64 v[0:1], v[0:1], 0, v[78:79]
	v_or_b32_e32 v79, s80, v34
	s_nop 1
	s_lshl_b32 s56, s54, 9
	v_lshl_add_u32 v79, v79, 6, v109
	s_add_i32 s56, s97, s56
	s_or_b32 s59, s80, 3
	s_or_b32 s60, s80, 4
	s_or_b32 s61, s80, 5
	s_or_b32 s62, s80, 6
	s_mov_b32 s100, 0x1600000
	s_mov_b32 s101, 0
	v_lshl_add_u64 v[204:205], v[8:9], 0, s[100:101]
	v_lshl_add_u64 v[206:207], v[102:103], 0, s[100:101]
	v_lshl_add_u64 v[208:209], v[0:1], 0, s[100:101]
	v_lshl_add_u64 v[210:211], v[4:5], 0, s[100:101]
	s_cmp_eq_u32 s99, s50
	s_cbranch_scc1 .Lpf2a_hit
	global_load_dwordx4 v[8:11], v[8:9], off offset:1024
	global_load_dword v52, v[102:103], off offset:3072
	global_load_dwordx4 v[0:3], v[0:1], off offset:512
	global_load_dwordx4 v[4:7], v[4:5], off offset:1024
	s_waitcnt vmcnt(0)
	s_branch .Lpf2a_join
.Lpf2a_hit:
	s_waitcnt vmcnt(4)
	v_mov_b32_e32 v8, v212
	v_mov_b32_e32 v9, v213
	v_mov_b32_e32 v10, v214
	v_mov_b32_e32 v11, v215
	v_mov_b32_e32 v52, v216
	v_mov_b32_e32 v0, v220
	v_mov_b32_e32 v1, v221
	v_mov_b32_e32 v2, v222
	v_mov_b32_e32 v3, v223
	v_mov_b32_e32 v4, v224
	v_mov_b32_e32 v5, v225
	v_mov_b32_e32 v6, v226
	v_mov_b32_e32 v7, v227
.Lpf2a_join:
	s_add_i32 s99, s50, s14
	s_cmpk_lt_i32 s99, 0x600
	s_cbranch_scc0 .Lpf2a_nopf
	global_load_dwordx4 v[212:215], v[204:205], off offset:1024
	global_load_dword v216, v[206:207], off offset:3072
	global_load_dwordx4 v[220:223], v[208:209], off offset:512
	global_load_dwordx4 v[224:227], v[210:211], off offset:1024
	s_branch .Lpf2a_go
.Lpf2a_nopf:
	s_mov_b32 s99, -1
.Lpf2a_go:
	v_lshlrev_b32_e32 v102, 16, v52
	v_and_b32_e32 v103, 0xffff0000, v52
	ds_write_b64 v79, v[102:103]
	v_mov_b32_e32 v52, s56
	ds_read_b128 v[102:105], v52
	ds_read_b128 v[156:159], v52 offset:16
	ds_read_b128 v[160:163], v52 offset:32
	ds_read_b128 v[164:167], v52 offset:48
	s_mov_b32 s56, 0x3d800000
	s_waitcnt lgkmcnt(3)
	v_mul_f32_e32 v52, v103, v99
	v_fmac_f32_e32 v52, v102, v97
	v_fmac_f32_e32 v52, v104, v95
	s_waitcnt lgkmcnt(2)
	v_mul_f32_e32 v79, v157, v100
	s_waitcnt lgkmcnt(0)
	v_mov_b32_e32 v103, v164
	v_mov_b32_e32 v164, v161
	v_fmac_f32_e32 v52, v105, v93
	v_fmac_f32_e32 v79, v156, v98
	v_mov_b32_e32 v102, v160
	v_pk_mul_f32 v[104:105], v[164:165], v[18:19]
	v_fmac_f32_e32 v79, v158, v96
	v_pk_fma_f32 v[102:103], v[102:103], v[16:17], v[104:105]
	v_mov_b32_e32 v104, v162
	v_mov_b32_e32 v105, v166
	v_add_f32_e32 v52, v28, v52
	v_fmac_f32_e32 v79, v159, v94
	v_pk_fma_f32 v[102:103], v[104:105], v[14:15], v[102:103]
	v_mov_b32_e32 v166, v163
	v_add_f32_e32 v52, v52, v79
	v_pk_fma_f32 v[102:103], v[166:167], v[12:13], v[102:103]
	s_nop 0
	v_add_f32_e32 v52, v52, v102
	v_add_f32_e32 v52, v52, v103
	v_min_f32_e32 v79, 0, v52
	v_mul_f32_e64 v52, |v52|, s20
	v_exp_f32_e32 v52, v52
	s_nop 0
	v_add_f32_e32 v52, 1.0, v52
	v_cmp_gt_f32_e32 vcc, s21, v52
	s_nop 1
	v_cndmask_b32_e64 v81, 0, 32, vcc
	v_ldexp_f32 v52, v52, v81
	v_log_f32_e32 v52, v52
	s_nop 0
	v_mul_f32_e32 v81, 0x3f317217, v52
	v_fma_f32 v81, v52, s8, -v81
	v_fmac_f32_e32 v81, 0x3377d1cf, v52
	v_fmac_f32_e32 v81, 0x3f317217, v52
	v_cmp_lt_f32_e64 s[78:79], |v52|, s9
	s_nop 1
	v_cndmask_b32_e64 v52, v52, v81, s[78:79]
	v_cndmask_b32_e32 v81, 0, v152, vcc
	v_sub_f32_e32 v52, v52, v81
	v_sub_f32_e32 v52, v79, v52
	v_fma_f32 v52, v52, s56, 0
	s_or_b32 s56, s80, 1
	s_lshl_b32 s57, s56, 6
	s_add_i32 s57, s97, s57
	v_mov_b32_e32 v79, s57
	ds_read_b128 v[102:105], v79
	ds_read_b128 v[156:159], v79 offset:16
	ds_read_b128 v[160:163], v79 offset:32
	ds_read_b128 v[164:167], v79 offset:48
	s_or_b32 s57, s80, 2
	s_waitcnt lgkmcnt(3)
	v_mul_f32_e32 v79, v99, v103
	v_fmac_f32_e32 v79, v97, v102
	v_fmac_f32_e32 v79, v95, v104
	s_waitcnt lgkmcnt(2)
	v_mul_f32_e32 v81, v100, v157
	s_waitcnt lgkmcnt(0)
	v_mov_b32_e32 v103, v164
	v_mov_b32_e32 v164, v161
	v_fmac_f32_e32 v79, v93, v105
	v_fmac_f32_e32 v81, v98, v156
	v_mov_b32_e32 v102, v160
	v_pk_mul_f32 v[104:105], v[18:19], v[164:165]
	v_fmac_f32_e32 v81, v96, v158
	v_pk_fma_f32 v[102:103], v[16:17], v[102:103], v[104:105]
	v_mov_b32_e32 v104, v162
	v_mov_b32_e32 v105, v166
	v_add_f32_e32 v79, v28, v79
	v_fmac_f32_e32 v81, v94, v159
	v_pk_fma_f32 v[102:103], v[14:15], v[104:105], v[102:103]
	v_mov_b32_e32 v166, v163
	v_add_f32_e32 v79, v79, v81
	v_pk_fma_f32 v[102:103], v[12:13], v[166:167], v[102:103]
	s_lshl_b32 s58, s57, 6
	v_add_f32_e32 v79, v79, v102
	v_add_f32_e32 v79, v79, v103
	v_min_f32_e32 v81, 0, v79
	v_mul_f32_e64 v79, |v79|, s20
	v_exp_f32_e32 v79, v79
	s_add_i32 s58, s97, s58
	v_add_f32_e32 v79, 1.0, v79
	v_cmp_gt_f32_e32 vcc, s21, v79
	s_nop 1
	v_cndmask_b32_e64 v83, 0, 32, vcc
	v_ldexp_f32 v79, v79, v83
	v_log_f32_e32 v79, v79
	s_nop 0
	v_mul_f32_e32 v83, 0x3f317217, v79
	v_fma_f32 v83, v79, s8, -v83
	v_fmac_f32_e32 v83, 0x3377d1cf, v79
	v_fmac_f32_e32 v83, 0x3f317217, v79
	v_cmp_lt_f32_e64 s[78:79], |v79|, s9
	s_nop 1
	v_cndmask_b32_e64 v79, v79, v83, s[78:79]
	v_cndmask_b32_e32 v83, 0, v152, vcc
	v_sub_f32_e32 v79, v79, v83
	v_sub_f32_e32 v79, v81, v79
	v_mov_b32_e32 v81, s58
	ds_read_b128 v[102:105], v81
	ds_read_b128 v[156:159], v81 offset:16
	ds_read_b128 v[160:163], v81 offset:32
	ds_read_b128 v[164:167], v81 offset:48
	s_lshl_b32 s58, s59, 6
	s_waitcnt lgkmcnt(3)
; #define LAS __attribute__((address_space(3)))
; __device__ __forceinline__ float logsig(float x) { return fminf(x, 0.f) - __logf(1.f + __expf(-fabsf(x))); }
; template <int MODE>
; __device__ __forceinline__ void gla_chunk_item(int item, const u16* PROJ, u16* MIXIN, const float* wgate, const float* bgate, const float* ggla, float* GS, float* GDEC, const u16* GSB, LAS unsigned char* lds, GateW& gw_) {
;     ...
; #pragma unroll
;     for (int tt = 0; tt < 8; ++tt) {
;         const LAS f32x4* gp = (const LAS f32x4*)(GLR + (seg * 8 + tt) * 16);
;         float logit = gw_.bgd;
; #pragma unroll
;         for (int r4 = 0; r4 < 4; ++r4) { const f32x4 gv = gp[r4]; logit += gv.x * gw_.wg[4 * r4] + gv.y * gw_.wg[4 * r4 + 1] + gv.z * gw_.wg[4 * r4 + 2] + gv.w * gw_.wg[4 * r4 + 3]; }
;         run += logsig(logit) * (1.f / 16.f); bl[tt] = run;
;     }
	v_mov_b32_e32 v168, v102
	s_waitcnt lgkmcnt(2)
	v_mov_b32_e32 v169, v156
	v_mov_b32_e32 v156, v103
	v_pk_mul_f32 v[102:103], v[26:27], v[156:157]
	v_mov_b32_e32 v156, v104
	v_pk_fma_f32 v[102:103], v[24:25], v[168:169], v[102:103]
	v_mov_b32_e32 v157, v158
	v_pk_fma_f32 v[102:103], v[22:23], v[156:157], v[102:103]
	v_mov_b32_e32 v158, v105
	v_pk_fma_f32 v[102:103], v[20:21], v[158:159], v[102:103]
	s_add_i32 s58, s97, s58
	v_add_f32_e32 v81, v28, v102
	v_add_f32_e32 v81, v81, v103
	s_waitcnt lgkmcnt(0)
	v_mov_b32_e32 v103, v164
	v_mov_b32_e32 v164, v161
	v_mov_b32_e32 v102, v160
	v_pk_mul_f32 v[104:105], v[18:19], v[164:165]
	v_fmamk_f32 v79, v79, 0x3d800000, v52
	v_pk_fma_f32 v[102:103], v[16:17], v[102:103], v[104:105]
	v_mov_b32_e32 v104, v162
	v_mov_b32_e32 v105, v166
	v_pk_fma_f32 v[102:103], v[14:15], v[104:105], v[102:103]
	v_mov_b32_e32 v166, v163
	v_pk_fma_f32 v[102:103], v[12:13], v[166:167], v[102:103]
	s_nop 0
	v_add_f32_e32 v81, v81, v102
	v_add_f32_e32 v81, v81, v103
	v_min_f32_e32 v83, 0, v81
	v_mul_f32_e64 v81, |v81|, s20
	v_exp_f32_e32 v81, v81
	s_nop 0
	v_add_f32_e32 v81, 1.0, v81
	v_cmp_gt_f32_e32 vcc, s21, v81
	s_nop 1
	v_cndmask_b32_e64 v85, 0, 32, vcc
	v_ldexp_f32 v81, v81, v85
	v_log_f32_e32 v81, v81
	s_nop 0
	v_mul_f32_e32 v85, 0x3f317217, v81
	v_fma_f32 v85, v81, s8, -v85
	v_fmac_f32_e32 v85, 0x3377d1cf, v81
	v_fmac_f32_e32 v85, 0x3f317217, v81
	v_cmp_lt_f32_e64 s[78:79], |v81|, s9
	s_nop 1
	v_cndmask_b32_e64 v81, v81, v85, s[78:79]
	v_cndmask_b32_e32 v85, 0, v152, vcc
	v_sub_f32_e32 v81, v81, v85
	v_sub_f32_e32 v81, v83, v81
	v_mov_b32_e32 v83, s58
	ds_read_b128 v[102:105], v83
	ds_read_b128 v[156:159], v83 offset:16
	ds_read_b128 v[160:163], v83 offset:32
	ds_read_b128 v[164:167], v83 offset:48
	s_lshl_b32 s58, s60, 6
	s_waitcnt lgkmcnt(3)
	v_mov_b32_e32 v168, v102
	s_waitcnt lgkmcnt(2)
	v_mov_b32_e32 v169, v156
	v_mov_b32_e32 v156, v103
	v_pk_mul_f32 v[102:103], v[26:27], v[156:157]
	v_mov_b32_e32 v156, v104
	v_pk_fma_f32 v[102:103], v[24:25], v[168:169], v[102:103]
	v_mov_b32_e32 v157, v158
	v_pk_fma_f32 v[102:103], v[22:23], v[156:157], v[102:103]
	v_mov_b32_e32 v158, v105
	v_pk_fma_f32 v[102:103], v[20:21], v[158:159], v[102:103]
	s_add_i32 s58, s97, s58
	v_add_f32_e32 v83, v28, v102
	v_add_f32_e32 v83, v83, v103
	s_waitcnt lgkmcnt(0)
	v_mov_b32_e32 v103, v164
	v_mov_b32_e32 v164, v161
	v_mov_b32_e32 v102, v160
	v_pk_mul_f32 v[104:105], v[18:19], v[164:165]
	v_fmamk_f32 v81, v81, 0x3d800000, v79
	v_pk_fma_f32 v[102:103], v[16:17], v[102:103], v[104:105]
	v_mov_b32_e32 v104, v162
	v_mov_b32_e32 v105, v166
	v_pk_fma_f32 v[102:103], v[14:15], v[104:105], v[102:103]
	v_mov_b32_e32 v166, v163
	v_pk_fma_f32 v[102:103], v[12:13], v[166:167], v[102:103]
	s_nop 0
	v_add_f32_e32 v83, v83, v102
	v_add_f32_e32 v83, v83, v103
	v_min_f32_e32 v85, 0, v83
	v_mul_f32_e64 v83, |v83|, s20
	v_exp_f32_e32 v83, v83
	s_nop 0
	v_add_f32_e32 v83, 1.0, v83
	v_cmp_gt_f32_e32 vcc, s21, v83
	s_nop 1
	v_cndmask_b32_e64 v87, 0, 32, vcc
	v_ldexp_f32 v83, v83, v87
	v_log_f32_e32 v83, v83
	s_nop 0
	v_mul_f32_e32 v87, 0x3f317217, v83
	v_fma_f32 v87, v83, s8, -v87
	v_fmac_f32_e32 v87, 0x3377d1cf, v83
	v_fmac_f32_e32 v87, 0x3f317217, v83
	v_cmp_lt_f32_e64 s[78:79], |v83|, s9
	s_nop 1
	v_cndmask_b32_e64 v83, v83, v87, s[78:79]
	v_cndmask_b32_e32 v87, 0, v152, vcc
	v_sub_f32_e32 v83, v83, v87
	v_sub_f32_e32 v83, v85, v83
	v_mov_b32_e32 v85, s58
	ds_read_b128 v[102:105], v85
	ds_read_b128 v[156:159], v85 offset:16
	ds_read_b128 v[160:163], v85 offset:32
	ds_read_b128 v[164:167], v85 offset:48
	s_lshl_b32 s58, s61, 6
	s_waitcnt lgkmcnt(3)
	v_mov_b32_e32 v168, v102
	s_waitcnt lgkmcnt(2)
	v_mov_b32_e32 v169, v156
	v_mov_b32_e32 v156, v103
	v_pk_mul_f32 v[102:103], v[26:27], v[156:157]
	v_mov_b32_e32 v156, v104
	v_pk_fma_f32 v[102:103], v[24:25], v[168:169], v[102:103]
	v_mov_b32_e32 v157, v158
	v_pk_fma_f32 v[102:103], v[22:23], v[156:157], v[102:103]
	v_mov_b32_e32 v158, v105
	v_pk_fma_f32 v[102:103], v[20:21], v[158:159], v[102:103]
	s_add_i32 s58, s97, s58
	v_add_f32_e32 v85, v28, v102
	v_add_f32_e32 v85, v85, v103
	s_waitcnt lgkmcnt(0)
	v_mov_b32_e32 v103, v164
	v_mov_b32_e32 v164, v161
	v_mov_b32_e32 v102, v160
	v_pk_mul_f32 v[104:105], v[18:19], v[164:165]
	v_fmamk_f32 v83, v83, 0x3d800000, v81
	v_pk_fma_f32 v[102:103], v[16:17], v[102:103], v[104:105]
	v_mov_b32_e32 v104, v162
	v_mov_b32_e32 v105, v166
	v_pk_fma_f32 v[102:103], v[14:15], v[104:105], v[102:103]
	v_mov_b32_e32 v166, v163
	v_pk_fma_f32 v[102:103], v[12:13], v[166:167], v[102:103]
	s_nop 0
	v_add_f32_e32 v85, v85, v102
	v_add_f32_e32 v85, v85, v103
	v_min_f32_e32 v87, 0, v85
	v_mul_f32_e64 v85, |v85|, s20
	v_exp_f32_e32 v85, v85
	s_nop 0
	v_add_f32_e32 v85, 1.0, v85
	v_cmp_gt_f32_e32 vcc, s21, v85
	s_nop 1
	v_cndmask_b32_e64 v101, 0, 32, vcc
	v_ldexp_f32 v85, v85, v101
	v_log_f32_e32 v85, v85
	s_nop 0
	v_mul_f32_e32 v101, 0x3f317217, v85
	v_fma_f32 v101, v85, s8, -v101
	v_fmac_f32_e32 v101, 0x3377d1cf, v85
	v_fmac_f32_e32 v101, 0x3f317217, v85
	v_cmp_lt_f32_e64 s[78:79], |v85|, s9
	s_nop 1
	v_cndmask_b32_e64 v85, v85, v101, s[78:79]
	v_cndmask_b32_e32 v101, 0, v152, vcc
	v_sub_f32_e32 v85, v85, v101
	v_sub_f32_e32 v85, v87, v85
	v_mov_b32_e32 v87, s58
	ds_read_b128 v[102:105], v87
	ds_read_b128 v[156:159], v87 offset:16
	ds_read_b128 v[160:163], v87 offset:32
	ds_read_b128 v[164:167], v87 offset:48
	s_lshl_b32 s58, s62, 6
	s_waitcnt lgkmcnt(3)
	v_mov_b32_e32 v168, v102
	s_waitcnt lgkmcnt(2)
; #define LAS __attribute__((address_space(3)))
; __device__ __forceinline__ float logsig(float x) { return fminf(x, 0.f) - __logf(1.f + __expf(-fabsf(x))); }
; #define LBAR() do { asm volatile("s_waitcnt lgkmcnt(0)" ::: "memory"); __builtin_amdgcn_s_barrier(); asm volatile("" ::: "memory"); } while (0)
; template <int MODE>
; __device__ __forceinline__ void gla_chunk_item(int item, const u16* PROJ, u16* MIXIN, const float* wgate, const float* bgate, const float* ggla, float* GS, float* GDEC, const u16* GSB, LAS unsigned char* lds, GateW& gw_) {
;     ...
; #pragma unroll
;     for (int tt = 0; tt < 8; ++tt) {
;         const LAS f32x4* gp = (const LAS f32x4*)(GLR + (seg * 8 + tt) * 16);
;         float logit = gw_.bgd;
; #pragma unroll
;         for (int r4 = 0; r4 < 4; ++r4) { const f32x4 gv = gp[r4]; logit += gv.x * gw_.wg[4 * r4] + gv.y * gw_.wg[4 * r4 + 1] + gv.z * gw_.wg[4 * r4 + 2] + gv.w * gw_.wg[4 * r4 + 3]; }
;         run += logsig(logit) * (1.f / 16.f); bl[tt] = run;
;     }
;     SEG[seg * 64 + d] = run;
;     if (MODE == 1) *(LAS u32x4*)(RQ + qt_ * 64 + qd_) = qraw;
;     *(LAS u32x4*)(RK + qt_ * 64 + qd_) = kraw;
;     *(LAS u32x2*)(RV + vt_ * RP + ve_) = (u32x2){vraw0.x, vraw0.y}; *(LAS u32x2*)(RV + vt_ * RP + ve_ + 4) = (u32x2){vraw0.z, vraw0.w};
;     *(LAS u32x2*)(RV + (32 + vt_) * RP + ve_) = (u32x2){vraw1.x, vraw1.y}; *(LAS u32x2*)(RV + (32 + vt_) * RP + ve_ + 4) = (u32x2){vraw1.z, vraw1.w};
;     if (MODE == 1) {
; #pragma unroll
;         for (int i = 0; i < 2; ++i) { const int idx = tid + 512 * i; LAS u16* sp_ = SN + (idx >> 4) * RP + (idx & 15) * 8;
;             *(LAS u32x2*)sp_ = (u32x2){sraw[i].x, sraw[i].y}; *(LAS u32x2*)(sp_ + 4) = (u32x2){sraw[i].z, sraw[i].w}; }
;     }
;     LBAR();
	v_mov_b32_e32 v169, v156
	v_mov_b32_e32 v156, v103
	v_pk_mul_f32 v[102:103], v[26:27], v[156:157]
	v_mov_b32_e32 v156, v104
	v_pk_fma_f32 v[102:103], v[24:25], v[168:169], v[102:103]
	v_mov_b32_e32 v157, v158
	v_pk_fma_f32 v[102:103], v[22:23], v[156:157], v[102:103]
	v_mov_b32_e32 v158, v105
	v_pk_fma_f32 v[102:103], v[20:21], v[158:159], v[102:103]
	s_add_i32 s58, s97, s58
	v_add_f32_e32 v87, v28, v102
	v_add_f32_e32 v87, v87, v103
	s_waitcnt lgkmcnt(0)
	v_mov_b32_e32 v103, v164
	v_mov_b32_e32 v164, v161
	v_mov_b32_e32 v102, v160
	v_pk_mul_f32 v[104:105], v[18:19], v[164:165]
	v_fmamk_f32 v85, v85, 0x3d800000, v83
	v_pk_fma_f32 v[102:103], v[16:17], v[102:103], v[104:105]
	v_mov_b32_e32 v104, v162
	v_mov_b32_e32 v105, v166
	v_pk_fma_f32 v[102:103], v[14:15], v[104:105], v[102:103]
	v_mov_b32_e32 v166, v163
	v_pk_fma_f32 v[102:103], v[12:13], v[166:167], v[102:103]
	s_nop 0
	v_add_f32_e32 v87, v87, v102
	v_add_f32_e32 v87, v87, v103
	v_min_f32_e32 v101, 0, v87
	v_mul_f32_e64 v87, |v87|, s20
	v_exp_f32_e32 v87, v87
	s_nop 0
	v_add_f32_e32 v87, 1.0, v87
	v_cmp_gt_f32_e32 vcc, s21, v87
	s_nop 1
	v_cndmask_b32_e64 v102, 0, 32, vcc
	v_ldexp_f32 v87, v87, v102
	v_log_f32_e32 v87, v87
	s_nop 0
	v_mul_f32_e32 v102, 0x3f317217, v87
	v_fma_f32 v102, v87, s8, -v102
	v_fmac_f32_e32 v102, 0x3377d1cf, v87
	v_fmac_f32_e32 v102, 0x3f317217, v87
	v_cmp_lt_f32_e64 s[78:79], |v87|, s9
	s_nop 1
	v_cndmask_b32_e64 v87, v87, v102, s[78:79]
	v_cndmask_b32_e32 v102, 0, v152, vcc
	v_sub_f32_e32 v87, v87, v102
	v_sub_f32_e32 v87, v101, v87
	v_mov_b32_e32 v101, s58
	ds_read_b128 v[102:105], v101
	ds_read_b128 v[156:159], v101 offset:16
	ds_read_b128 v[160:163], v101 offset:32
	ds_read_b128 v[164:167], v101 offset:48
	s_or_b32 s58, s80, 7
	s_waitcnt lgkmcnt(3)
	v_mov_b32_e32 v168, v102
	s_waitcnt lgkmcnt(2)
	v_mov_b32_e32 v169, v156
	v_mov_b32_e32 v156, v103
	v_pk_mul_f32 v[26:27], v[26:27], v[156:157]
	s_lshl_b32 s63, s58, 6
	v_pk_fma_f32 v[24:25], v[24:25], v[168:169], v[26:27]
	v_mov_b32_e32 v26, v104
	v_mov_b32_e32 v27, v158
	v_pk_fma_f32 v[22:23], v[22:23], v[26:27], v[24:25]
	v_mov_b32_e32 v158, v105
	v_pk_fma_f32 v[20:21], v[20:21], v[158:159], v[22:23]
	s_add_i32 s63, s97, s63
	v_add_f32_e32 v20, v28, v20
	v_add_f32_e32 v24, v20, v21
	s_waitcnt lgkmcnt(0)
	v_mov_b32_e32 v21, v164
	v_mov_b32_e32 v164, v161
	v_mov_b32_e32 v20, v160
	v_pk_mul_f32 v[22:23], v[18:19], v[164:165]
	v_mov_b32_e32 v155, s63
	v_pk_fma_f32 v[20:21], v[16:17], v[20:21], v[22:23]
	v_mov_b32_e32 v22, v162
	v_mov_b32_e32 v23, v166
	v_pk_fma_f32 v[20:21], v[14:15], v[22:23], v[20:21]
	v_mov_b32_e32 v166, v163
	v_pk_fma_f32 v[20:21], v[12:13], v[166:167], v[20:21]
	v_fmamk_f32 v87, v87, 0x3d800000, v85
	v_add_f32_e32 v20, v24, v20
	v_add_f32_e32 v20, v20, v21
	v_min_f32_e32 v21, 0, v20
	v_mul_f32_e64 v20, |v20|, s20
	v_exp_f32_e32 v20, v20
	s_and_b32 s63, s55, 0x3fffffc0
	s_cmp_gt_u32 s55, 63
	v_add_f32_e32 v20, 1.0, v20
	v_cmp_gt_f32_e32 vcc, s21, v20
	s_nop 1
	v_cndmask_b32_e64 v22, 0, 32, vcc
	v_ldexp_f32 v20, v20, v22
	v_log_f32_e32 v20, v20
	s_nop 0
	v_mul_f32_e32 v22, 0x3f317217, v20
	v_fma_f32 v22, v20, s8, -v22
	v_fmac_f32_e32 v22, 0x3377d1cf, v20
	v_fmac_f32_e32 v22, 0x3f317217, v20
	v_cmp_lt_f32_e64 s[78:79], |v20|, s9
	s_nop 1
	v_cndmask_b32_e64 v20, v20, v22, s[78:79]
	v_cndmask_b32_e32 v22, 0, v152, vcc
	v_sub_f32_e32 v20, v20, v22
	v_sub_f32_e32 v101, v21, v20
	ds_read_b128 v[20:23], v155
	ds_read_b128 v[24:27], v155 offset:16
	ds_read_b128 v[102:105], v155 offset:32
	ds_read_b128 v[156:159], v155 offset:48
	s_waitcnt lgkmcnt(3)
	v_mul_f32_e32 v21, v99, v21
	v_fmac_f32_e32 v21, v97, v20
	v_fmac_f32_e32 v21, v95, v22
	v_fmac_f32_e32 v21, v93, v23
	v_add_f32_e32 v20, v28, v21
	s_waitcnt lgkmcnt(2)
	v_mul_f32_e32 v21, v100, v25
	v_fmac_f32_e32 v21, v98, v24
	v_fmac_f32_e32 v21, v96, v26
	v_fmac_f32_e32 v21, v94, v27
	v_add_f32_e32 v22, v20, v21
	s_waitcnt lgkmcnt(0)
	v_mov_b32_e32 v21, v156
	v_mov_b32_e32 v156, v103
	v_mov_b32_e32 v20, v102
	v_pk_mul_f32 v[18:19], v[18:19], v[156:157]
	s_nop 0
	v_pk_fma_f32 v[16:17], v[16:17], v[20:21], v[18:19]
	v_mov_b32_e32 v18, v104
	v_mov_b32_e32 v19, v158
	v_pk_fma_f32 v[14:15], v[14:15], v[18:19], v[16:17]
	v_mov_b32_e32 v158, v105
	v_pk_fma_f32 v[12:13], v[12:13], v[158:159], v[14:15]
	v_fmamk_f32 v15, v101, 0x3d800000, v87
	v_add_f32_e32 v12, v22, v12
	v_add_f32_e32 v12, v12, v13
	v_min_f32_e32 v13, 0, v12
	v_mul_f32_e64 v12, |v12|, s20
	v_exp_f32_e32 v12, v12
	v_lshl_add_u32 v16, s54, 10, v112
	v_lshl_add_u32 v17, s56, 7, v112
	v_lshl_add_u32 v18, s57, 7, v112
	v_add_f32_e32 v12, 1.0, v12
	v_cmp_gt_f32_e32 vcc, s21, v12
	v_lshl_add_u32 v19, s59, 7, v112
	v_lshl_add_u32 v20, s60, 7, v112
	v_cndmask_b32_e64 v14, 0, 32, vcc
	v_ldexp_f32 v12, v12, v14
	v_log_f32_e32 v12, v12
	v_lshl_add_u32 v21, s61, 7, v112
	v_lshl_add_u32 v22, s62, 7, v112
	v_mul_f32_e32 v14, 0x3f317217, v12
	v_fma_f32 v14, v12, s8, -v14
	v_fmac_f32_e32 v14, 0x3377d1cf, v12
	v_fmac_f32_e32 v14, 0x3f317217, v12
	v_cmp_lt_f32_e64 s[78:79], |v12|, s9
	s_nop 1
	v_cndmask_b32_e64 v12, v12, v14, s[78:79]
	v_cndmask_b32_e32 v14, 0, v152, vcc
	v_sub_f32_e32 v12, v12, v14
	v_sub_f32_e32 v12, v13, v12
	v_lshl_add_u32 v13, s63, 2, v33
	v_fmamk_f32 v12, v12, 0x3d800000, v15
	ds_write_b32 v13, v12
	ds_write_b128 v110, v[0:3] offset:45056
	v_add_u32_e32 v0, 0xd000, v111
	ds_write2_b64 v0, v[4:5], v[6:7] offset1:1
	v_add_u32_e32 v0, 0xf100, v111
	ds_write2_b64 v0, v[8:9], v[10:11] offset1:1
	s_waitcnt lgkmcnt(0)
	s_barrier
; #define LAS __attribute__((address_space(3)))
; __device__ __forceinline__ float bf2f(unsigned b) { return __uint_as_float(b << 16); }
; __device__ __forceinline__ unsigned pk2(float lo, float hi) { unsigned r; asm("v_cvt_pk_bf16_f32 %0, %1, %2" : "=v"(r) : "v"(lo), "v"(hi)); return r; }
; template <int MODE>
; __device__ __forceinline__ void gla_chunk_item(int item, const u16* PROJ, u16* MIXIN, const float* wgate, const float* bgate, const float* ggla, float* GS, float* GDEC, const u16* GSB, LAS unsigned char* lds, GateW& gw_) {
;     ...
;     float off = 0.f, tot = 0.f;
; #pragma unroll
;     for (int s = 0; s < 8; ++s) { const float v = SEG[s * 64 + d]; tot += v; off += (s < seg) ? v : 0.f; }
;     if (MODE == 0) {
;         float kd[8];
; #pragma unroll
;         for (int tt = 0; tt < 8; ++tt) kd[tt] = bf2f(RK[(seg * 8 + tt) * 64 + d]) * __expf(tot - (off + bl[tt]));
;         u32x4 kk; kk.x = pk2(kd[0], kd[1]); kk.y = pk2(kd[2], kd[3]); kk.z = pk2(kd[4], kd[5]); kk.w = pk2(kd[6], kd[7]);
;         *(LAS u32x4*)(KdT + d * LD + seg * 8) = kk;
;         if (seg == 0) GDEC[(size_t)item * 64 + d] = __expf(tot);
	ds_read2st64_b32 v[0:1], v33 offset1:1
	s_cselect_b64 vcc, -1, 0
	s_cmpk_gt_u32 s55, 0x7f
	s_cselect_b64 s[90:91], -1, 0
	s_cmpk_gt_u32 s55, 0xbf
	s_waitcnt lgkmcnt(0)
	v_add_f32_e32 v0, 0, v0
	v_cndmask_b32_e32 v2, 0, v0, vcc
	v_add_f32_e32 v3, v0, v1
	v_cndmask_b32_e64 v0, 0, v1, s[90:91]
	v_add_f32_e32 v2, v2, v0
	ds_read2st64_b32 v[0:1], v33 offset0:2 offset1:3
	s_cselect_b64 s[88:89], -1, 0
	s_cmpk_gt_u32 s55, 0xff
	s_cselect_b64 s[86:87], -1, 0
	s_cmpk_gt_u32 s55, 0x13f
	s_waitcnt lgkmcnt(0)
	v_add_f32_e32 v3, v3, v0
	v_cndmask_b32_e64 v0, 0, v0, s[88:89]
	v_add_f32_e32 v0, v2, v0
	v_add_f32_e32 v2, v3, v1
	v_cndmask_b32_e64 v1, 0, v1, s[86:87]
	v_add_f32_e32 v3, v0, v1
	ds_read2st64_b32 v[0:1], v33 offset0:4 offset1:5
	s_cselect_b64 s[84:85], -1, 0
	s_cmpk_gt_u32 s55, 0x17f
	s_cselect_b64 s[82:83], -1, 0
	s_cmpk_gt_u32 s55, 0x1bf
	s_waitcnt lgkmcnt(0)
	v_add_f32_e32 v2, v2, v0
	v_cndmask_b32_e64 v0, 0, v0, s[84:85]
	v_add_f32_e32 v0, v3, v0
	v_add_f32_e32 v2, v2, v1
	v_cndmask_b32_e64 v1, 0, v1, s[82:83]
	v_add_f32_e32 v3, v0, v1
	ds_read2st64_b32 v[0:1], v33 offset0:6 offset1:7
	s_cselect_b64 s[80:81], -1, 0
	s_cmpk_gt_u32 s55, 0x1ff
	s_cselect_b64 s[78:79], -1, 0
	s_and_b64 vcc, exec, vcc
	s_waitcnt lgkmcnt(0)
	v_add_f32_e32 v14, v2, v0
	v_cndmask_b32_e64 v0, 0, v0, s[80:81]
	v_add_f32_e32 v0, v3, v0
	v_cndmask_b32_e64 v2, 0, v1, s[78:79]
	v_add_f32_e32 v3, v0, v2
	ds_read_u16 v0, v16 offset:45056
	v_mov_b32_e32 v2, v1
	v_add_f32_e32 v5, v52, v3
	v_add_f32_e32 v6, v81, v3
	v_add_f32_e32 v7, v83, v3
	s_waitcnt lgkmcnt(0)
	v_lshlrev_b32_e32 v4, 16, v0
	v_pk_add_f32 v[0:1], v[14:15], v[2:3]
	v_add_f32_e32 v8, v85, v3
	v_sub_f32_e32 v2, v0, v5
	v_mul_f32_e32 v2, 0x3fb8aa3b, v2
	v_exp_f32_e32 v2, v2
	v_add_f32_e32 v5, v79, v3
	v_sub_f32_e32 v5, v0, v5
	v_mul_f32_e32 v5, 0x3fb8aa3b, v5
	v_mul_f32_e32 v2, v2, v4
	ds_read_u16 v4, v17 offset:45056
	v_exp_f32_e32 v5, v5
	v_sub_f32_e32 v6, v0, v6
	v_mul_f32_e32 v6, 0x3fb8aa3b, v6
	v_exp_f32_e32 v6, v6
	s_waitcnt lgkmcnt(0)
	v_lshlrev_b32_e32 v4, 16, v4
	v_mul_f32_e32 v4, v5, v4
	ds_read_u16 v5, v18 offset:45056
	v_sub_f32_e32 v7, v0, v7
	v_mul_f32_e32 v7, 0x3fb8aa3b, v7
	v_exp_f32_e32 v7, v7
	v_sub_f32_e32 v8, v0, v8
	s_waitcnt lgkmcnt(0)
	v_lshlrev_b32_e32 v5, 16, v5
	v_mul_f32_e32 v5, v6, v5
	ds_read_u16 v6, v19 offset:45056
	v_mul_f32_e32 v8, 0x3fb8aa3b, v8
	v_exp_f32_e32 v8, v8
	v_add_f32_e32 v9, v87, v3
	v_sub_f32_e32 v9, v0, v9
	s_waitcnt lgkmcnt(0)
	v_lshlrev_b32_e32 v6, 16, v6
	v_mul_f32_e32 v6, v7, v6
	ds_read_u16 v7, v20 offset:45056
	v_mul_f32_e32 v9, 0x3fb8aa3b, v9
	v_exp_f32_e32 v9, v9
	v_sub_f32_e32 v1, v0, v1
	v_mul_f32_e32 v1, 0x3fb8aa3b, v1
	s_waitcnt lgkmcnt(0)
	v_lshlrev_b32_e32 v7, 16, v7
	v_mul_f32_e32 v7, v8, v7
	ds_read_u16 v8, v21 offset:45056
	v_exp_f32_e32 v1, v1
	v_add_f32_e32 v3, v12, v3
	v_sub_f32_e32 v3, v0, v3
	v_mul_f32_e32 v3, 0x3fb8aa3b, v3
	s_waitcnt lgkmcnt(0)
	v_lshlrev_b32_e32 v8, 16, v8
	v_mul_f32_e32 v8, v9, v8
	ds_read_u16 v9, v22 offset:45056
	v_exp_f32_e32 v3, v3
	v_cvt_pk_bf16_f32 v2, v2, v4
	v_cvt_pk_bf16_f32 v4, v7, v8
	s_waitcnt lgkmcnt(0)
	v_lshlrev_b32_e32 v9, 16, v9
	v_mul_f32_e32 v1, v1, v9
	v_lshl_add_u32 v9, s58, 7, v112
	ds_read_u16 v9, v9 offset:45056
	s_waitcnt lgkmcnt(0)
	v_lshlrev_b32_e32 v9, 16, v9
	v_mul_f32_e32 v9, v3, v9
	v_cvt_pk_bf16_f32 v3, v5, v6
	v_cvt_pk_bf16_f32 v5, v1, v9
	v_lshl_add_u32 v1, s54, 4, v113
	ds_write_b128 v1, v[2:5] offset:18432
	s_cbranch_vccnz .LBB0_246
	v_mul_f32_e32 v0, 0x3fb8aa3b, v0
	v_exp_f32_e32 v2, v0
	s_lshl_b64 s[56:57], s[6:7], 8
	v_lshl_add_u64 v[0:1], v[62:63], 0, s[56:57]
	global_store_dword v[0:1], v2, off
